# combo4 + recurrence units: M1 score-chain LDS reads prefetched three steps ahead (was 16 serialized LDS round trips per 64-step block)
# speedup vs baseline: 1.0066x; 1.0013x over previous
; #define LAS __attribute__((address_space(3)))
; __device__ __forceinline__ unsigned cvt_pk_bf16(float lo, float hi) { unsigned r; asm volatile("v_cvt_pk_bf16_f32 %0, %1, %2" : "=v"(r) : "v"(lo), "v"(hi)); return r; }
; #define S2_FETCH(cc, bufi) do { const LAS unsigned char* qrow_ = lds + S2_Q + (16 * (cc) + x) * S2_ROW; \
;             _Pragma("unroll") for (int i = 0; i < 4; ++i) { qa[bufi][2 * i] = *(const LAS u32x2*)(qrow_ + 64 * i + 8 * g); qa[bufi][2 * i + 1] = *(const LAS u32x2*)(qrow_ + 64 * i + 32 + 8 * g); } } while (0)
; __device__ __forceinline__ void scan_unit(LAS unsigned char* lds, bf16* UB, bf16* UC, const ScanBufs sb, unsigned* pre_cnt, unsigned pre_want, unsigned* scan_cnt, int type, int bl, int h, int j, int tid, int wave, int lane) {
;     ...
;         s16x4 sa[4], vf[4];
; #pragma unroll
;         for (int cc = 0; cc < 4; ++cc) {
;             const LAS unsigned char* qrow = lds + S2_Q + (16 * cc + x) * S2_ROW;
;             const LAS unsigned char* prow = lds + S2_KP + (16 * cc + x) * S2_ROW;
;             f32x4 st = (f32x4){0.f, 0.f, 0.f, 0.f};
; #pragma unroll
;             for (int i = 0; i < 4; ++i) st = __builtin_amdgcn_mfma_f32_16x16x32_bf16(*(const LAS bf16x8*)(prow + 64 * i + 16 * g), *(const LAS bf16x8*)(qrow + 64 * i + 16 * g), st, 0, 0, 0);
; #pragma unroll
;             for (int r = 0; r < 4; ++r) if (4 * g + r > x) st[r] = 0.f;
;             const u32x2 sw = (u32x2){cvt_pk_bf16(st[0], st[1]), cvt_pk_bf16(st[2], st[3])};
;             sa[cc] = __builtin_bit_cast(s16x4, sw);
;             vf[cc] = __builtin_bit_cast(s16x4, __builtin_amdgcn_ds_read_tr16_b64_v4i16((LAS v4i16_t*)(lds + S2_VT + (16 * cc + 4 * g + (x >> 2)) * S2_VROW + (16 * wave + 4 * (x & 3)) * 2)));
;         }
;         u32x2 qa[2][8];
;     ...
;         S2_FETCH(0, 0);
; #pragma unroll
;         for (int cc = 0; cc < 4; ++cc) {
;             const int bi = cc & 1;
;             f32x4 dv[8]; s16x4 ka[8];
; #pragma unroll
;             for (int rb = 0; rb < 8; ++rb) { dv[rb] = *(const LAS f32x4*)(lds + S2_D + (cc * 128 + 16 * rb + 4 * g) * 4); ka[rb] = __builtin_bit_cast(s16x4, __builtin_amdgcn_ds_read_tr16_b64_v4i16((LAS v4i16_t*)(lds + S2_KP + (16 * cc + 4 * g + (x >> 2)) * S2_ROW + (16 * rb + 4 * (x & 3)) * 2))); }
.LBB0_550:
	v_add_u32_e32 v68, 0x1000, v201
	ds_read_b64_tr_b16 v[152:153], v199 offset:34816
	ds_read_b64_tr_b16 v[148:149], v199 offset:39424
	ds_read_b64_tr_b16 v[144:145], v199 offset:44032
	ds_read_b64_tr_b16 v[140:141], v199 offset:48640
	ds_read_b128 v[232:235], v198 offset:17408
	ds_read_b128 v[236:239], v198
	ds_read_b128 v[240:243], v198 offset:17472
	ds_read_b128 v[244:247], v198 offset:64
	ds_read_b128 v[248:251], v198 offset:17536
	ds_read_b128 v[208:211], v198 offset:128
	s_waitcnt lgkmcnt(4)
	v_mfma_f32_16x16x32_bf16 v[56:59], v[232:235], v[236:239], 0
	ds_read_b128 v[232:235], v198 offset:17600
	ds_read_b128 v[236:239], v198 offset:192
	s_waitcnt lgkmcnt(4)
	v_mfma_f32_16x16x32_bf16 v[56:59], v[240:243], v[244:247], v[56:59]
	ds_read_b128 v[240:243], v198 offset:21760
	ds_read_b128 v[244:247], v198 offset:4352
	s_waitcnt lgkmcnt(4)
	v_mfma_f32_16x16x32_bf16 v[56:59], v[248:251], v[208:211], v[56:59]
	ds_read_b128 v[248:251], v198 offset:21824
	ds_read_b128 v[208:211], v198 offset:4416
	s_waitcnt lgkmcnt(4)
	v_mfma_f32_16x16x32_bf16 v[56:59], v[232:235], v[236:239], v[56:59]
	ds_read_b128 v[232:235], v198 offset:21888
	ds_read_b128 v[236:239], v198 offset:4480
	v_mov_b32_e32 v60, s61
	s_nop 6
	v_cndmask_b32_e32 v60, v56, v60, vcc
	v_cndmask_b32_e64 v56, v60, v56, s[44:45]
	v_cndmask_b32_e64 v57, 0, v57, s[44:45]
	v_cndmask_b32_e64 v58, v58, 0, s[46:47]
	v_cndmask_b32_e64 v59, v59, 0, s[48:49]
	v_cvt_pk_bf16_f32 v150, v56, v57
	v_cvt_pk_bf16_f32 v151, v58, v59
	s_waitcnt lgkmcnt(4)
	v_mfma_f32_16x16x32_bf16 v[56:59], v[240:243], v[244:247], 0
	ds_read_b128 v[240:243], v198 offset:21952
	ds_read_b128 v[244:247], v198 offset:4544
	s_waitcnt lgkmcnt(4)
	v_mfma_f32_16x16x32_bf16 v[56:59], v[248:251], v[208:211], v[56:59]
	ds_read_b128 v[248:251], v198 offset:26112
	ds_read_b128 v[208:211], v198 offset:8704
	s_waitcnt lgkmcnt(4)
	v_mfma_f32_16x16x32_bf16 v[56:59], v[232:235], v[236:239], v[56:59]
	ds_read_b128 v[232:235], v198 offset:26176
	ds_read_b128 v[236:239], v198 offset:8768
	s_waitcnt lgkmcnt(4)
	v_mfma_f32_16x16x32_bf16 v[56:59], v[240:243], v[244:247], v[56:59]
	ds_read_b128 v[240:243], v198 offset:26240
	ds_read_b128 v[244:247], v198 offset:8832
	v_mov_b32_e32 v60, s61
	s_nop 6
	v_cndmask_b32_e32 v60, v56, v60, vcc
	v_cndmask_b32_e64 v56, v60, v56, s[44:45]
	v_cndmask_b32_e64 v57, 0, v57, s[44:45]
	v_cndmask_b32_e64 v58, v58, 0, s[46:47]
	v_cndmask_b32_e64 v59, v59, 0, s[48:49]
	v_cvt_pk_bf16_f32 v146, v56, v57
	v_cvt_pk_bf16_f32 v147, v58, v59
	s_waitcnt lgkmcnt(4)
	v_mfma_f32_16x16x32_bf16 v[56:59], v[248:251], v[208:211], 0
	ds_read_b128 v[248:251], v198 offset:26304
	ds_read_b128 v[208:211], v198 offset:8896
	s_waitcnt lgkmcnt(4)
	v_mfma_f32_16x16x32_bf16 v[56:59], v[232:235], v[236:239], v[56:59]
	ds_read_b128 v[232:235], v200 offset:17408
	ds_read_b128 v[236:239], v200
	s_waitcnt lgkmcnt(4)
	v_mfma_f32_16x16x32_bf16 v[56:59], v[240:243], v[244:247], v[56:59]
	ds_read_b128 v[240:243], v200 offset:17472
	ds_read_b128 v[244:247], v200 offset:64
	s_waitcnt lgkmcnt(4)
	v_mfma_f32_16x16x32_bf16 v[56:59], v[248:251], v[208:211], v[56:59]
	ds_read_b128 v[248:251], v200 offset:17536
	ds_read_b128 v[208:211], v200 offset:128
	v_mov_b32_e32 v60, s61
	s_nop 6
	v_cndmask_b32_e32 v60, v56, v60, vcc
	v_cndmask_b32_e64 v56, v60, v56, s[44:45]
	v_cndmask_b32_e64 v57, 0, v57, s[44:45]
	v_cndmask_b32_e64 v58, v58, 0, s[46:47]
	v_cndmask_b32_e64 v59, v59, 0, s[48:49]
	v_cvt_pk_bf16_f32 v142, v56, v57
	v_cvt_pk_bf16_f32 v143, v58, v59
	s_waitcnt lgkmcnt(4)
	v_mfma_f32_16x16x32_bf16 v[56:59], v[232:235], v[236:239], 0
	ds_read_b128 v[232:235], v200 offset:17600
	ds_read_b128 v[236:239], v200 offset:192
	s_waitcnt lgkmcnt(4)
	v_mfma_f32_16x16x32_bf16 v[56:59], v[240:243], v[244:247], v[56:59]
	s_waitcnt lgkmcnt(2)
	v_mfma_f32_16x16x32_bf16 v[56:59], v[248:251], v[208:211], v[56:59]
	s_waitcnt lgkmcnt(0)
	v_mfma_f32_16x16x32_bf16 v[56:59], v[232:235], v[236:239], v[56:59]
	v_mov_b32_e32 v60, s61
	s_nop 6
	v_cndmask_b32_e32 v60, v56, v60, vcc
	v_cndmask_b32_e64 v56, v60, v56, s[44:45]
	v_cndmask_b32_e64 v57, 0, v57, s[44:45]
	v_cndmask_b32_e64 v58, v58, 0, s[46:47]
	v_cndmask_b32_e64 v59, v59, 0, s[48:49]
	v_cvt_pk_bf16_f32 v138, v56, v57
	v_cvt_pk_bf16_f32 v139, v58, v59
	ds_read2_b64 v[116:119], v201 offset1:4
	ds_read2_b64 v[112:115], v201 offset0:8 offset1:12
	ds_read2_b64 v[108:111], v201 offset0:16 offset1:20
	ds_read2_b64 v[104:107], v201 offset0:24 offset1:28
	ds_read_b128 v[100:103], v188 offset:53248
	ds_read_b128 v[96:99], v188 offset:53312
	ds_read_b64_tr_b16 v[184:185], v202 offset:17408
	ds_read_b64_tr_b16 v[166:167], v202 offset:17440
	ds_read_b128 v[92:95], v188 offset:53376
	ds_read_b64_tr_b16 v[164:165], v202 offset:17472
	ds_read_b128 v[88:91], v188 offset:53440
	ds_read_b64_tr_b16 v[162:163], v202 offset:17504
	ds_read_b128 v[72:75], v188 offset:53504
	ds_read_b64_tr_b16 v[160:161], v202 offset:17536
	ds_read_b128 v[64:67], v188 offset:53568
	ds_read_b64_tr_b16 v[158:159], v202 offset:17568
	ds_read_b128 v[60:63], v188 offset:53632
	ds_read_b64_tr_b16 v[156:157], v202 offset:17600
	ds_read_b128 v[56:59], v188 offset:53696
	ds_read_b64_tr_b16 v[154:155], v202 offset:17632
	ds_read2_b64 v[84:87], v68 offset0:32 offset1:36
	ds_read2_b64 v[80:83], v68 offset0:40 offset1:44
	ds_read2_b64 v[76:79], v68 offset0:48 offset1:52
	ds_read2_b64 v[68:71], v68 offset0:56 offset1:60
	v_cvt_pk_bf16_f32 v204, v44, v45
	v_cvt_pk_bf16_f32 v205, v46, v47
	v_cvt_pk_bf16_f32 v206, v52, v53
	v_cvt_pk_bf16_f32 v207, v54, v55
	s_waitcnt lgkmcnt(14)
; #define LAS __attribute__((address_space(3)))
; __device__ __forceinline__ unsigned cvt_pk_bf16(float lo, float hi) { unsigned r; asm volatile("v_cvt_pk_bf16_f32 %0, %1, %2" : "=v"(r) : "v"(lo), "v"(hi)); return r; }
; __device__ __forceinline__ void scan_unit(LAS unsigned char* lds, bf16* UB, bf16* UC, const ScanBufs sb, unsigned* pre_cnt, unsigned pre_want, unsigned* scan_cnt, int type, int bl, int h, int j, int tid, int wave, int lane) {
;     ...
;         for (int cc = 0; cc < 4; ++cc) {
;             const int bi = cc & 1;
;             f32x4 dv[8]; s16x4 ka[8];
; #pragma unroll
;             for (int rb = 0; rb < 8; ++rb) { dv[rb] = *(const LAS f32x4*)(lds + S2_D + (cc * 128 + 16 * rb + 4 * g) * 4); ka[rb] = __builtin_bit_cast(s16x4, __builtin_amdgcn_ds_read_tr16_b64_v4i16((LAS v4i16_t*)(lds + S2_KP + (16 * cc + 4 * g + (x >> 2)) * S2_ROW + (16 * rb + 4 * (x & 3)) * 2))); }
;             if (cc < 3) { if (bi == 0) S2_FETCH(cc + 1, 1); else S2_FETCH(cc + 1, 0); }
;             f32x4 o0 = (f32x4){0.f, 0.f, 0.f, 0.f}, o1 = (f32x4){0.f, 0.f, 0.f, 0.f};
; #pragma unroll
;             for (int i = 0; i < 4; ++i) {
;                 const u32x4 sfw = (u32x4){cvt_pk_bf16(S[2 * i][0], S[2 * i][1]), cvt_pk_bf16(S[2 * i][2], S[2 * i][3]), cvt_pk_bf16(S[2 * i + 1][0], S[2 * i + 1][1]), cvt_pk_bf16(S[2 * i + 1][2], S[2 * i + 1][3])};
;                 const u32x4 qaw = (u32x4){qa[bi][2 * i].x, qa[bi][2 * i].y, qa[bi][2 * i + 1].x, qa[bi][2 * i + 1].y};
;                 if (i & 1) o1 = __builtin_amdgcn_mfma_f32_16x16x32_bf16(__builtin_bit_cast(bf16x8, qaw), __builtin_bit_cast(bf16x8, sfw), o1, 0, 0, 0);
;                 else       o0 = __builtin_amdgcn_mfma_f32_16x16x32_bf16(__builtin_bit_cast(bf16x8, qaw), __builtin_bit_cast(bf16x8, sfw), o0, 0, 0, 0);
;             }
; #pragma unroll
;             for (int rb = 0; rb < 8; ++rb) S[rb] = __builtin_amdgcn_mfma_f32_16x16x16bf16_1k(ka[rb], vf[cc], S[rb], 0, 0, 0) * dv[rb];
;             o0 = __builtin_amdgcn_mfma_f32_16x16x16bf16_1k(sa[cc], vf[cc], o0, 0, 0, 0);
;             o0 = o0 + o1;
; #pragma unroll
;             for (int r = 0; r < 4; ++r) *(LAS unsigned short*)(lds + S2_O + (16 * cc + 4 * g + r) * S2_ROW + (16 * wave + x) * 2) = (unsigned short)(cvt_pk_bf16(o0[r], 0.f) & 0xffffu);
;         }
	v_mfma_f32_16x16x16_bf16 v[44:47], v[184:185], v[152:153], v[44:47]
	v_mfma_f32_16x16x32_bf16 v[116:119], v[116:119], v[204:207], 0
	v_cvt_pk_bf16_f32 v204, v48, v49
	v_cvt_pk_bf16_f32 v205, v50, v51
	v_cvt_pk_bf16_f32 v206, v40, v41
	v_cvt_pk_bf16_f32 v207, v42, v43
	v_mfma_f32_16x16x16_bf16 v[52:55], v[166:167], v[152:153], v[52:55]
	s_nop 5
	v_mul_f32_e64 v46, v102, v46
	v_mul_f32_e64 v47, v103, v47
	v_pk_mul_f32 v[44:45], v[100:101], v[44:45]
	v_mfma_f32_16x16x32_bf16 v[112:115], v[112:115], v[204:207], 0
	v_cvt_pk_bf16_f32 v204, v36, v37
	v_cvt_pk_bf16_f32 v205, v38, v39
	v_cvt_pk_bf16_f32 v206, v28, v29
	v_cvt_pk_bf16_f32 v207, v30, v31
	s_waitcnt lgkmcnt(8)
	v_mfma_f32_16x16x16_bf16 v[28:31], v[158:159], v[152:153], v[28:31]
	v_mul_f32_e64 v54, v98, v54
	v_mul_f32_e64 v55, v99, v55
	v_pk_mul_f32 v[52:53], v[96:97], v[52:53]
	v_mfma_f32_16x16x32_bf16 v[108:111], v[108:111], v[204:207], v[116:119]
	v_cvt_pk_bf16_f32 v116, v32, v33
	v_cvt_pk_bf16_f32 v117, v34, v35
	v_cvt_pk_bf16_f32 v118, v24, v25
	v_cvt_pk_bf16_f32 v119, v26, v27
	s_waitcnt lgkmcnt(4)
	v_mfma_f32_16x16x16_bf16 v[24:27], v[154:155], v[152:153], v[24:27]
	s_nop 1
	v_mul_f32_e64 v66, v66, v30
	v_mul_f32_e64 v67, v67, v31
	v_pk_mul_f32 v[64:65], v[64:65], v[28:29]
	v_mfma_f32_16x16x32_bf16 v[104:107], v[104:107], v[116:119], v[112:115]
	v_mfma_f32_16x16x16_bf16 v[28:31], v[156:157], v[152:153], v[32:35]
	s_nop 2
	v_mul_f32_e64 v34, v58, v26
	v_mul_f32_e64 v35, v59, v27
	v_pk_mul_f32 v[32:33], v[56:57], v[24:25]
	v_mfma_f32_16x16x16_bf16 v[24:27], v[150:151], v[152:153], v[108:111]
	v_mfma_f32_16x16x16_bf16 v[48:51], v[164:165], v[152:153], v[48:51]
	v_mfma_f32_16x16x16_bf16 v[40:43], v[162:163], v[152:153], v[40:43]
	s_nop 5
	v_add_f32_e64 v24, v104, v24
	v_add_f32_e64 v25, v105, v25
	v_pk_add_f32 v[26:27], v[106:107], v[26:27]
	v_cvt_pk_bf16_f32 v24, v24, v169
	v_mfma_f32_16x16x16_bf16 v[36:39], v[160:161], v[152:153], v[36:39]
	ds_write_b16 v192, v24 offset:55296
	v_cvt_pk_bf16_f32 v24, v25, v169
	ds_write_b16 v192, v24 offset:55568
	v_cvt_pk_bf16_f32 v24, v26, v169
	ds_write_b16 v203, v24 offset:55296
	v_cvt_pk_bf16_f32 v24, v27, v169
	ds_write_b16 v203, v24 offset:55568
	v_add_u32_e32 v24, 0x2000, v201
	v_pk_mul_f32 v[94:95], v[94:95], v[50:51]
	v_pk_mul_f32 v[92:93], v[92:93], v[48:49]
	v_pk_mul_f32 v[42:43], v[90:91], v[42:43]
	v_pk_mul_f32 v[40:41], v[88:89], v[40:41]
	v_pk_mul_f32 v[74:75], v[74:75], v[38:39]
	v_pk_mul_f32 v[72:73], v[72:73], v[36:37]
	v_pk_mul_f32 v[90:91], v[62:63], v[30:31]
	v_pk_mul_f32 v[88:89], v[60:61], v[28:29]
	ds_read_b128 v[56:59], v188 offset:53760
	ds_read_b128 v[60:63], v188 offset:53824
	ds_read_b64_tr_b16 v[162:163], v202 offset:21760
	ds_read_b64_tr_b16 v[164:165], v202 offset:21792
	ds_read_b128 v[108:111], v188 offset:53888
	ds_read_b64_tr_b16 v[166:167], v202 offset:21824
	ds_read_b128 v[112:115], v188 offset:53952
	ds_read_b64_tr_b16 v[170:171], v202 offset:21856
	ds_read_b128 v[116:119], v188 offset:54016
	ds_read_b64_tr_b16 v[172:173], v202 offset:21888
	ds_read_b128 v[150:153], v188 offset:54080
	ds_read_b64_tr_b16 v[184:185], v202 offset:21920
	ds_read_b128 v[100:103], v188 offset:54144
	ds_read_b64_tr_b16 v[106:107], v202 offset:21952
	ds_read_b128 v[96:99], v188 offset:54208
	ds_read_b64_tr_b16 v[104:105], v202 offset:21984
	ds_read2_b64 v[48:51], v24 offset0:64 offset1:68
	ds_read2_b64 v[36:39], v24 offset0:72 offset1:76
	ds_read2_b64 v[28:31], v24 offset0:80 offset1:84
	ds_read2_b64 v[24:27], v24 offset0:88 offset1:92
	v_cvt_pk_bf16_f32 v154, v44, v45
	v_cvt_pk_bf16_f32 v155, v46, v47
	v_cvt_pk_bf16_f32 v156, v52, v53
	v_cvt_pk_bf16_f32 v157, v54, v55
	s_waitcnt lgkmcnt(14)
	v_mfma_f32_16x16x16_bf16 v[44:47], v[162:163], v[148:149], v[44:47]
	v_mfma_f32_16x16x32_bf16 v[84:87], v[84:87], v[154:157], 0
	v_cvt_pk_bf16_f32 v154, v92, v93
	v_cvt_pk_bf16_f32 v155, v94, v95
	v_cvt_pk_bf16_f32 v156, v40, v41
	v_cvt_pk_bf16_f32 v157, v42, v43
	s_waitcnt lgkmcnt(12)
	v_mfma_f32_16x16x16_bf16 v[40:43], v[170:171], v[148:149], v[40:43]
	v_mfma_f32_16x16x32_bf16 v[80:83], v[80:83], v[154:157], 0
	v_cvt_pk_bf16_f32 v154, v72, v73
	v_cvt_pk_bf16_f32 v155, v74, v75
	v_cvt_pk_bf16_f32 v156, v64, v65
	v_cvt_pk_bf16_f32 v157, v66, v67
	s_nop 0
	v_mfma_f32_16x16x32_bf16 v[154:157], v[76:79], v[154:157], v[84:87]
	v_cvt_pk_bf16_f32 v76, v88, v89
	v_cvt_pk_bf16_f32 v77, v90, v91
	v_cvt_pk_bf16_f32 v78, v32, v33
	v_cvt_pk_bf16_f32 v79, v34, v35
	s_waitcnt lgkmcnt(4)
; #define LAS __attribute__((address_space(3)))
; __device__ __forceinline__ unsigned cvt_pk_bf16(float lo, float hi) { unsigned r; asm volatile("v_cvt_pk_bf16_f32 %0, %1, %2" : "=v"(r) : "v"(lo), "v"(hi)); return r; }
; __device__ __forceinline__ void scan_unit(LAS unsigned char* lds, bf16* UB, bf16* UC, const ScanBufs sb, unsigned* pre_cnt, unsigned pre_want, unsigned* scan_cnt, int type, int bl, int h, int j, int tid, int wave, int lane) {
;     ...
;         for (int cc = 0; cc < 4; ++cc) {
;             const int bi = cc & 1;
;             f32x4 dv[8]; s16x4 ka[8];
; #pragma unroll
;             for (int rb = 0; rb < 8; ++rb) { dv[rb] = *(const LAS f32x4*)(lds + S2_D + (cc * 128 + 16 * rb + 4 * g) * 4); ka[rb] = __builtin_bit_cast(s16x4, __builtin_amdgcn_ds_read_tr16_b64_v4i16((LAS v4i16_t*)(lds + S2_KP + (16 * cc + 4 * g + (x >> 2)) * S2_ROW + (16 * rb + 4 * (x & 3)) * 2))); }
;             if (cc < 3) { if (bi == 0) S2_FETCH(cc + 1, 1); else S2_FETCH(cc + 1, 0); }
;             f32x4 o0 = (f32x4){0.f, 0.f, 0.f, 0.f}, o1 = (f32x4){0.f, 0.f, 0.f, 0.f};
; #pragma unroll
;             for (int i = 0; i < 4; ++i) {
;                 const u32x4 sfw = (u32x4){cvt_pk_bf16(S[2 * i][0], S[2 * i][1]), cvt_pk_bf16(S[2 * i][2], S[2 * i][3]), cvt_pk_bf16(S[2 * i + 1][0], S[2 * i + 1][1]), cvt_pk_bf16(S[2 * i + 1][2], S[2 * i + 1][3])};
;                 const u32x4 qaw = (u32x4){qa[bi][2 * i].x, qa[bi][2 * i].y, qa[bi][2 * i + 1].x, qa[bi][2 * i + 1].y};
;                 if (i & 1) o1 = __builtin_amdgcn_mfma_f32_16x16x32_bf16(__builtin_bit_cast(bf16x8, qaw), __builtin_bit_cast(bf16x8, sfw), o1, 0, 0, 0);
;                 else       o0 = __builtin_amdgcn_mfma_f32_16x16x32_bf16(__builtin_bit_cast(bf16x8, qaw), __builtin_bit_cast(bf16x8, sfw), o0, 0, 0, 0);
;             }
; #pragma unroll
;             for (int rb = 0; rb < 8; ++rb) S[rb] = __builtin_amdgcn_mfma_f32_16x16x16bf16_1k(ka[rb], vf[cc], S[rb], 0, 0, 0) * dv[rb];
;             o0 = __builtin_amdgcn_mfma_f32_16x16x16bf16_1k(sa[cc], vf[cc], o0, 0, 0, 0);
;             o0 = o0 + o1;
; #pragma unroll
;             for (int r = 0; r < 4; ++r) *(LAS unsigned short*)(lds + S2_O + (16 * cc + 4 * g + r) * S2_ROW + (16 * wave + x) * 2) = (unsigned short)(cvt_pk_bf16(o0[r], 0.f) & 0xffffu);
;         }
	v_mfma_f32_16x16x16_bf16 v[32:35], v[104:105], v[148:149], v[32:35]
	s_nop 0
	v_mul_f32_e64 v86, v58, v46
	v_mul_f32_e64 v87, v59, v47
	v_pk_mul_f32 v[84:85], v[56:57], v[44:45]
	v_mfma_f32_16x16x32_bf16 v[158:161], v[68:71], v[76:79], v[80:83]
	v_mul_f32_e64 v70, v114, v42
	v_mul_f32_e64 v71, v115, v43
	v_pk_mul_f32 v[68:69], v[112:113], v[40:41]
	v_mfma_f32_16x16x16_bf16 v[44:47], v[164:165], v[148:149], v[52:55]
	v_mfma_f32_16x16x16_bf16 v[40:43], v[172:173], v[148:149], v[72:75]
	s_nop 6
	v_mul_f32_e64 v82, v62, v46
	v_mul_f32_e64 v83, v63, v47
	v_pk_mul_f32 v[80:81], v[60:61], v[44:45]
	v_pk_mul_f32 v[62:63], v[118:119], v[42:43]
	v_pk_mul_f32 v[60:61], v[116:117], v[40:41]
	v_mfma_f32_16x16x16_bf16 v[40:43], v[184:185], v[148:149], v[64:67]
	s_nop 2
	v_mul_f32_e64 v66, v98, v34
	v_mul_f32_e64 v67, v99, v35
	v_pk_mul_f32 v[64:65], v[96:97], v[32:33]
	v_mfma_f32_16x16x16_bf16 v[32:35], v[146:147], v[148:149], v[154:157]
	s_nop 0
	v_mul_f32_e64 v58, v152, v42
	v_mul_f32_e64 v59, v153, v43
	v_pk_mul_f32 v[56:57], v[150:151], v[40:41]
	v_mfma_f32_16x16x16_bf16 v[44:47], v[166:167], v[148:149], v[92:95]
	v_mfma_f32_16x16x16_bf16 v[40:43], v[106:107], v[148:149], v[88:91]
	s_nop 1
	v_add_f32_e64 v32, v158, v32
	v_add_f32_e64 v33, v159, v33
	v_pk_add_f32 v[34:35], v[160:161], v[34:35]
	v_cvt_pk_bf16_f32 v32, v32, v169
	ds_write_b16 v192, v32 offset:59648
	v_cvt_pk_bf16_f32 v32, v33, v169
	ds_write_b16 v192, v32 offset:59920
	v_cvt_pk_bf16_f32 v32, v34, v169
	ds_write_b16 v192, v32 offset:60192
	v_cvt_pk_bf16_f32 v32, v35, v169
	ds_write_b16 v192, v32 offset:60464
	v_add_u32_e32 v32, 0x3000, v201
	v_pk_mul_f32 v[78:79], v[110:111], v[46:47]
	v_pk_mul_f32 v[76:77], v[108:109], v[44:45]
	v_pk_mul_f32 v[74:75], v[102:103], v[42:43]
	v_pk_mul_f32 v[72:73], v[100:101], v[40:41]
	ds_read_b128 v[100:103], v188 offset:54272
	ds_read_b128 v[104:107], v188 offset:54336
	ds_read_b64_tr_b16 v[154:155], v202 offset:26112
	ds_read_b64_tr_b16 v[156:157], v202 offset:26144
	ds_read_b128 v[108:111], v188 offset:54400
	ds_read_b64_tr_b16 v[158:159], v202 offset:26176
	ds_read_b128 v[112:115], v188 offset:54464
	ds_read_b64_tr_b16 v[160:161], v202 offset:26208
	ds_read_b128 v[116:119], v188 offset:54528
	ds_read_b64_tr_b16 v[162:163], v202 offset:26240
	ds_read_b128 v[146:149], v188 offset:54592
	ds_read_b64_tr_b16 v[164:165], v202 offset:26272
	ds_read_b128 v[92:95], v188 offset:54656
	ds_read_b64_tr_b16 v[98:99], v202 offset:26304
	ds_read_b128 v[88:91], v188 offset:54720
	ds_read_b64_tr_b16 v[96:97], v202 offset:26336
	ds_read2_b64 v[52:55], v32 offset0:96 offset1:100
	ds_read2_b64 v[44:47], v32 offset0:104 offset1:108
	ds_read2_b64 v[40:43], v32 offset0:112 offset1:116
	ds_read2_b64 v[32:35], v32 offset0:120 offset1:124
	v_cvt_pk_bf16_f32 v150, v84, v85
	v_cvt_pk_bf16_f32 v151, v86, v87
	v_cvt_pk_bf16_f32 v152, v80, v81
	v_cvt_pk_bf16_f32 v153, v82, v83
	s_waitcnt lgkmcnt(14)
	v_mfma_f32_16x16x32_bf16 v[48:51], v[48:51], v[150:153], 0
	v_cvt_pk_bf16_f32 v150, v76, v77
	v_cvt_pk_bf16_f32 v151, v78, v79
	v_cvt_pk_bf16_f32 v152, v68, v69
	v_cvt_pk_bf16_f32 v153, v70, v71
	s_waitcnt lgkmcnt(12)
	v_mfma_f32_16x16x16_bf16 v[68:71], v[160:161], v[144:145], v[68:71]
	v_mfma_f32_16x16x32_bf16 v[36:39], v[36:39], v[150:153], 0
	v_cvt_pk_bf16_f32 v150, v60, v61
	v_cvt_pk_bf16_f32 v151, v62, v63
	v_cvt_pk_bf16_f32 v152, v56, v57
	v_cvt_pk_bf16_f32 v153, v58, v59
	s_waitcnt lgkmcnt(10)
	v_mfma_f32_16x16x16_bf16 v[60:63], v[162:163], v[144:145], v[60:63]
	s_nop 4
	v_mul_f32_e64 v70, v114, v70
	v_mul_f32_e64 v71, v115, v71
	v_pk_mul_f32 v[68:69], v[112:113], v[68:69]
	v_mfma_f32_16x16x32_bf16 v[48:51], v[28:31], v[150:153], v[48:51]
	v_cvt_pk_bf16_f32 v28, v72, v73
	v_cvt_pk_bf16_f32 v29, v74, v75
	v_cvt_pk_bf16_f32 v30, v64, v65
	v_cvt_pk_bf16_f32 v31, v66, v67
	v_mfma_f32_16x16x16_bf16 v[48:51], v[142:143], v[144:145], v[48:51]
	v_mul_f32_e64 v62, v118, v62
	v_mul_f32_e64 v63, v119, v63
	v_pk_mul_f32 v[60:61], v[116:117], v[60:61]
	v_mfma_f32_16x16x32_bf16 v[150:153], v[24:27], v[28:31], v[36:39]
	v_mfma_f32_16x16x16_bf16 v[24:27], v[154:155], v[144:145], v[84:87]
	v_mfma_f32_16x16x16_bf16 v[28:31], v[156:157], v[144:145], v[80:83]
	s_nop 5
	v_add_f32_e64 v48, v150, v48
	v_add_f32_e64 v49, v151, v49
	v_pk_add_f32 v[50:51], v[152:153], v[50:51]
	v_cvt_pk_bf16_f32 v48, v48, v169
	s_waitcnt lgkmcnt(8)
	v_mfma_f32_16x16x16_bf16 v[56:59], v[164:165], v[144:145], v[56:59]
	ds_write_b16 v192, v48 offset:64000
	v_cvt_pk_bf16_f32 v48, v49, v169
	ds_write_b16 v192, v48 offset:64272
	s_waitcnt lgkmcnt(8)
	v_mfma_f32_16x16x16_bf16 v[72:75], v[98:99], v[144:145], v[72:75]
	v_cvt_pk_bf16_f32 v48, v50, v169
	ds_write_b16 v192, v48 offset:64544
	v_cvt_pk_bf16_f32 v48, v51, v169
	s_waitcnt lgkmcnt(7)
; #define LAS __attribute__((address_space(3)))
; __device__ __forceinline__ void scan_unit(LAS unsigned char* lds, bf16* UB, bf16* UC, const ScanBufs sb, unsigned* pre_cnt, unsigned pre_want, unsigned* scan_cnt, int type, int bl, int h, int j, int tid, int wave, int lane) {
;     ...
;         for (int cc = 0; cc < 4; ++cc) {
;             const int bi = cc & 1;
;             f32x4 dv[8]; s16x4 ka[8];
; #pragma unroll
;             for (int rb = 0; rb < 8; ++rb) { dv[rb] = *(const LAS f32x4*)(lds + S2_D + (cc * 128 + 16 * rb + 4 * g) * 4); ka[rb] = __builtin_bit_cast(s16x4, __builtin_amdgcn_ds_read_tr16_b64_v4i16((LAS v4i16_t*)(lds + S2_KP + (16 * cc + 4 * g + (x >> 2)) * S2_ROW + (16 * rb + 4 * (x & 3)) * 2))); }
;             if (cc < 3) { if (bi == 0) S2_FETCH(cc + 1, 1); else S2_FETCH(cc + 1, 0); }
;             f32x4 o0 = (f32x4){0.f, 0.f, 0.f, 0.f}, o1 = (f32x4){0.f, 0.f, 0.f, 0.f};
; #pragma unroll
;             for (int i = 0; i < 4; ++i) {
;                 const u32x4 sfw = (u32x4){cvt_pk_bf16(S[2 * i][0], S[2 * i][1]), cvt_pk_bf16(S[2 * i][2], S[2 * i][3]), cvt_pk_bf16(S[2 * i + 1][0], S[2 * i + 1][1]), cvt_pk_bf16(S[2 * i + 1][2], S[2 * i + 1][3])};
;                 const u32x4 qaw = (u32x4){qa[bi][2 * i].x, qa[bi][2 * i].y, qa[bi][2 * i + 1].x, qa[bi][2 * i + 1].y};
;                 if (i & 1) o1 = __builtin_amdgcn_mfma_f32_16x16x32_bf16(__builtin_bit_cast(bf16x8, qaw), __builtin_bit_cast(bf16x8, sfw), o1, 0, 0, 0);
;                 else       o0 = __builtin_amdgcn_mfma_f32_16x16x32_bf16(__builtin_bit_cast(bf16x8, qaw), __builtin_bit_cast(bf16x8, sfw), o0, 0, 0, 0);
;             }
; #pragma unroll
;             for (int rb = 0; rb < 8; ++rb) S[rb] = __builtin_amdgcn_mfma_f32_16x16x16bf16_1k(ka[rb], vf[cc], S[rb], 0, 0, 0) * dv[rb];
;             o0 = __builtin_amdgcn_mfma_f32_16x16x16bf16_1k(sa[cc], vf[cc], o0, 0, 0, 0);
;             o0 = o0 + o1;
; #pragma unroll
;             for (int r = 0; r < 4; ++r) *(LAS unsigned short*)(lds + S2_O + (16 * cc + 4 * g + r) * S2_ROW + (16 * wave + x) * 2) = (unsigned short)(cvt_pk_bf16(o0[r], 0.f) & 0xffffu);
;         }
;     ...
;         __syncthreads();
; #pragma unroll
;         for (int k = 0; k < 2; ++k) { const int ch = tid + 512 * k, row = ch >> 4, c16 = ch & 15;
;             st_wt128(vdst + (rowb + (size_t)tb * 64 + row) * ld + c16 * 8, *(const LAS u32x4*)(lds + S2_O + row * S2_ROW + c16 * 16)); }
	v_mfma_f32_16x16x16_bf16 v[64:67], v[96:97], v[144:145], v[64:67]
	ds_write_b16 v192, v48 offset:64816
	v_pk_mul_f32 v[26:27], v[102:103], v[26:27]
	v_pk_mul_f32 v[24:25], v[100:101], v[24:25]
	v_mfma_f32_16x16x16_bf16 v[36:39], v[158:159], v[144:145], v[76:79]
	v_mul_f32_e64 v30, v106, v30
	v_mul_f32_e64 v31, v107, v31
	v_pk_mul_f32 v[28:29], v[104:105], v[28:29]
	v_pk_mul_f32 v[58:59], v[148:149], v[58:59]
	v_pk_mul_f32 v[56:57], v[146:147], v[56:57]
	v_pk_mul_f32 v[74:75], v[94:95], v[74:75]
	v_pk_mul_f32 v[72:73], v[92:93], v[72:73]
	v_pk_mul_f32 v[66:67], v[90:91], v[66:67]
	v_pk_mul_f32 v[64:65], v[88:89], v[64:65]
	ds_read_b128 v[48:51], v188 offset:54784
	ds_read_b128 v[76:79], v188 offset:54848
	ds_read_b64_tr_b16 v[112:113], v202 offset:30464
	ds_read_b64_tr_b16 v[114:115], v202 offset:30496
	ds_read_b128 v[80:83], v188 offset:54912
	ds_read_b64_tr_b16 v[116:117], v202 offset:30528
	ds_read_b128 v[84:87], v188 offset:54976
	ds_read_b64_tr_b16 v[118:119], v202 offset:30560
	ds_read_b128 v[88:91], v188 offset:55040
	ds_read_b64_tr_b16 v[142:143], v202 offset:30592
	ds_read_b128 v[92:95], v188 offset:55104
	ds_read_b64_tr_b16 v[144:145], v202 offset:30624
	ds_read_b128 v[96:99], v188 offset:55168
	ds_read_b64_tr_b16 v[146:147], v202 offset:30656
	ds_read_b128 v[100:103], v188 offset:55232
	ds_read_b64_tr_b16 v[148:149], v202 offset:30688
	v_cvt_pk_bf16_f32 v104, v24, v25
	v_cvt_pk_bf16_f32 v105, v26, v27
	v_cvt_pk_bf16_f32 v106, v28, v29
	v_cvt_pk_bf16_f32 v107, v30, v31
	v_pk_mul_f32 v[38:39], v[110:111], v[38:39]
	v_pk_mul_f32 v[36:37], v[108:109], v[36:37]
	s_waitcnt lgkmcnt(14)
	v_mfma_f32_16x16x32_bf16 v[52:55], v[52:55], v[104:107], 0
	v_cvt_pk_bf16_f32 v104, v36, v37
	v_cvt_pk_bf16_f32 v105, v38, v39
	v_cvt_pk_bf16_f32 v106, v68, v69
	v_cvt_pk_bf16_f32 v107, v70, v71
	s_waitcnt lgkmcnt(13)
	v_mfma_f32_16x16x16_bf16 v[24:27], v[112:113], v[140:141], v[24:27]
	v_mfma_f32_16x16x32_bf16 v[44:47], v[44:47], v[104:107], 0
	v_cvt_pk_bf16_f32 v104, v60, v61
	v_cvt_pk_bf16_f32 v105, v62, v63
	v_cvt_pk_bf16_f32 v106, v56, v57
	v_cvt_pk_bf16_f32 v107, v58, v59
	s_nop 0
	v_mfma_f32_16x16x32_bf16 v[104:107], v[40:43], v[104:107], v[52:55]
	v_cvt_pk_bf16_f32 v40, v72, v73
	v_cvt_pk_bf16_f32 v41, v74, v75
	v_cvt_pk_bf16_f32 v42, v64, v65
	v_cvt_pk_bf16_f32 v43, v66, v67
	s_nop 0
	v_mfma_f32_16x16x32_bf16 v[108:111], v[32:35], v[40:43], v[44:47]
	s_nop 3
	v_mul_f32_e64 v46, v50, v26
	v_mul_f32_e64 v47, v51, v27
	v_pk_mul_f32 v[44:45], v[48:49], v[24:25]
	s_waitcnt lgkmcnt(12)
	v_mfma_f32_16x16x16_bf16 v[24:27], v[114:115], v[140:141], v[28:31]
	s_nop 7
	v_pk_mul_f32 v[54:55], v[78:79], v[26:27]
	v_pk_mul_f32 v[52:53], v[76:77], v[24:25]
	s_waitcnt lgkmcnt(10)
	v_mfma_f32_16x16x16_bf16 v[24:27], v[116:117], v[140:141], v[36:39]
	s_nop 7
	v_pk_mul_f32 v[50:51], v[82:83], v[26:27]
	v_pk_mul_f32 v[48:49], v[80:81], v[24:25]
	s_waitcnt lgkmcnt(8)
	v_mfma_f32_16x16x16_bf16 v[24:27], v[118:119], v[140:141], v[68:71]
	s_nop 7
	v_pk_mul_f32 v[42:43], v[86:87], v[26:27]
	v_pk_mul_f32 v[40:41], v[84:85], v[24:25]
	s_waitcnt lgkmcnt(6)
	v_mfma_f32_16x16x16_bf16 v[24:27], v[142:143], v[140:141], v[60:63]
	s_nop 2
	v_lshl_add_u64 v[60:61], v[136:137], 0, s[12:13]
	v_add_co_u32_e64 v60, s[52:53], s63, v60
	s_nop 2
	v_pk_mul_f32 v[38:39], v[90:91], v[26:27]
	v_pk_mul_f32 v[36:37], v[88:89], v[24:25]
	s_waitcnt lgkmcnt(4)
	v_mfma_f32_16x16x16_bf16 v[24:27], v[144:145], v[140:141], v[56:59]
	v_addc_co_u32_e64 v61, s[52:53], 0, v61, s[52:53]
	v_mfma_f32_16x16x16_bf16 v[56:59], v[138:139], v[140:141], v[104:107]
	s_nop 5
	v_mul_f32_e64 v30, v94, v26
	v_mul_f32_e64 v31, v95, v27
	v_pk_add_f32 v[56:57], v[108:109], v[56:57]
	v_pk_add_f32 v[58:59], v[110:111], v[58:59]
	v_cvt_pk_bf16_f32 v56, v56, v169
	ds_write_b16 v193, v56 offset:13056
	v_cvt_pk_bf16_f32 v56, v57, v169
	ds_write_b16 v193, v56 offset:13328
	v_cvt_pk_bf16_f32 v56, v58, v169
	ds_write_b16 v193, v56 offset:13600
	v_cvt_pk_bf16_f32 v56, v59, v169
	ds_write_b16 v193, v56 offset:13872
	v_add_u32_e32 v56, v189, v190
	s_waitcnt lgkmcnt(0)
	s_barrier
	ds_read_b128 v[56:59], v56 offset:55296
	v_pk_mul_f32 v[28:29], v[92:93], v[24:25]
	v_mfma_f32_16x16x16_bf16 v[24:27], v[146:147], v[140:141], v[72:75]
	s_waitcnt lgkmcnt(0)
	global_store_dwordx2 v[60:61], v[56:57], off offset:2048 sc1
	global_store_dwordx2 v[60:61], v[58:59], off offset:2056 sc1
	v_add_u32_e32 v56, v189, v191
	s_nop 3
	v_pk_mul_f32 v[34:35], v[98:99], v[26:27]
	v_pk_mul_f32 v[32:33], v[96:97], v[24:25]
	v_mfma_f32_16x16x16_bf16 v[24:27], v[148:149], v[140:141], v[64:67]
	ds_read_b128 v[56:59], v56 offset:55296
	v_lshl_add_u64 v[60:61], v[134:135], 0, s[12:13]
	s_add_u32 s12, s12, 0x70000
	v_add_co_u32_e64 v60, s[52:53], s63, v60
	s_addc_u32 s13, s13, 0
	s_add_i32 s60, s60, 64
	s_nop 1
	v_pk_mul_f32 v[26:27], v[102:103], v[26:27]
	v_pk_mul_f32 v[24:25], v[100:101], v[24:25]
	v_addc_co_u32_e64 v61, s[52:53], 0, v61, s[52:53]
	s_cmp_eq_u32 s12, 0x1c00000
	s_waitcnt lgkmcnt(0)
	global_store_dwordx2 v[60:61], v[56:57], off offset:2048 sc1
	global_store_dwordx2 v[60:61], v[58:59], off offset:2056 sc1
	s_cbranch_scc1 .LBB0_553

; #define LAS __attribute__((address_space(3)))
; __device__ __forceinline__ unsigned cvt_pk_bf16(float lo, float hi) { unsigned r; asm volatile("v_cvt_pk_bf16_f32 %0, %1, %2" : "=v"(r) : "v"(lo), "v"(hi)); return r; }
; #define S2_FETCH(cc, bufi) do { const LAS unsigned char* qrow_ = lds + S2_Q + (16 * (cc) + x) * S2_ROW; \
;             _Pragma("unroll") for (int i = 0; i < 4; ++i) { qa[bufi][2 * i] = *(const LAS u32x2*)(qrow_ + 64 * i + 8 * g); qa[bufi][2 * i + 1] = *(const LAS u32x2*)(qrow_ + 64 * i + 32 + 8 * g); } } while (0)
; __device__ __forceinline__ void scan_unit(LAS unsigned char* lds, bf16* UB, bf16* UC, const ScanBufs sb, unsigned* pre_cnt, unsigned pre_want, unsigned* scan_cnt, int type, int bl, int h, int j, int tid, int wave, int lane) {
;     ...
;         s16x4 sa[4], vf[4];
; #pragma unroll
;         for (int cc = 0; cc < 4; ++cc) {
;             const LAS unsigned char* qrow = lds + S2_Q + (16 * cc + x) * S2_ROW;
;             const LAS unsigned char* prow = lds + S2_KP + (16 * cc + x) * S2_ROW;
;             f32x4 st = (f32x4){0.f, 0.f, 0.f, 0.f};
; #pragma unroll
;             for (int i = 0; i < 4; ++i) st = __builtin_amdgcn_mfma_f32_16x16x32_bf16(*(const LAS bf16x8*)(prow + 64 * i + 16 * g), *(const LAS bf16x8*)(qrow + 64 * i + 16 * g), st, 0, 0, 0);
; #pragma unroll
;             for (int r = 0; r < 4; ++r) if (4 * g + r > x) st[r] = 0.f;
;             const u32x2 sw = (u32x2){cvt_pk_bf16(st[0], st[1]), cvt_pk_bf16(st[2], st[3])};
;             sa[cc] = __builtin_bit_cast(s16x4, sw);
;             vf[cc] = __builtin_bit_cast(s16x4, __builtin_amdgcn_ds_read_tr16_b64_v4i16((LAS v4i16_t*)(lds + S2_VT + (16 * cc + 4 * g + (x >> 2)) * S2_VROW + (16 * wave + 4 * (x & 3)) * 2)));
;         }
;         u32x2 qa[2][8];
;     ...
;         S2_FETCH(0, 0);
; #pragma unroll
;         for (int cc = 0; cc < 4; ++cc) {
;             const int bi = cc & 1;
;             f32x4 dv[8]; s16x4 ka[8];
; #pragma unroll
;             for (int rb = 0; rb < 8; ++rb) { dv[rb] = *(const LAS f32x4*)(lds + S2_D + (cc * 128 + 16 * rb + 4 * g) * 4); ka[rb] = __builtin_bit_cast(s16x4, __builtin_amdgcn_ds_read_tr16_b64_v4i16((LAS v4i16_t*)(lds + S2_KP + (16 * cc + 4 * g + (x >> 2)) * S2_ROW + (16 * rb + 4 * (x & 3)) * 2))); }
.LBB0_571:
	v_add_u32_e32 v68, 0x1000, v201
	ds_read_b64_tr_b16 v[152:153], v199 offset:34816
	ds_read_b64_tr_b16 v[148:149], v199 offset:39424
	ds_read_b64_tr_b16 v[144:145], v199 offset:44032
	ds_read_b64_tr_b16 v[140:141], v199 offset:48640
	ds_read_b128 v[232:235], v198 offset:17408
	ds_read_b128 v[236:239], v198
	ds_read_b128 v[240:243], v198 offset:17472
	ds_read_b128 v[244:247], v198 offset:64
	ds_read_b128 v[248:251], v198 offset:17536
	ds_read_b128 v[208:211], v198 offset:128
	s_waitcnt lgkmcnt(4)
	v_mfma_f32_16x16x32_bf16 v[56:59], v[232:235], v[236:239], 0
	ds_read_b128 v[232:235], v198 offset:17600
	ds_read_b128 v[236:239], v198 offset:192
	s_waitcnt lgkmcnt(4)
	v_mfma_f32_16x16x32_bf16 v[56:59], v[240:243], v[244:247], v[56:59]
	ds_read_b128 v[240:243], v198 offset:21760
	ds_read_b128 v[244:247], v198 offset:4352
	s_waitcnt lgkmcnt(4)
	v_mfma_f32_16x16x32_bf16 v[56:59], v[248:251], v[208:211], v[56:59]
	ds_read_b128 v[248:251], v198 offset:21824
	ds_read_b128 v[208:211], v198 offset:4416
	s_waitcnt lgkmcnt(4)
	v_mfma_f32_16x16x32_bf16 v[56:59], v[232:235], v[236:239], v[56:59]
	ds_read_b128 v[232:235], v198 offset:21888
	ds_read_b128 v[236:239], v198 offset:4480
	v_mov_b32_e32 v60, s61
	s_nop 6
	v_cndmask_b32_e32 v60, v56, v60, vcc
	v_cndmask_b32_e64 v56, v60, v56, s[44:45]
	v_cndmask_b32_e64 v57, 0, v57, s[44:45]
	v_cndmask_b32_e64 v58, v58, 0, s[46:47]
	v_cndmask_b32_e64 v59, v59, 0, s[48:49]
	v_cvt_pk_bf16_f32 v150, v56, v57
	v_cvt_pk_bf16_f32 v151, v58, v59
	s_waitcnt lgkmcnt(4)
	v_mfma_f32_16x16x32_bf16 v[56:59], v[240:243], v[244:247], 0
	ds_read_b128 v[240:243], v198 offset:21952
	ds_read_b128 v[244:247], v198 offset:4544
	s_waitcnt lgkmcnt(4)
	v_mfma_f32_16x16x32_bf16 v[56:59], v[248:251], v[208:211], v[56:59]
	ds_read_b128 v[248:251], v198 offset:26112
	ds_read_b128 v[208:211], v198 offset:8704
	s_waitcnt lgkmcnt(4)
	v_mfma_f32_16x16x32_bf16 v[56:59], v[232:235], v[236:239], v[56:59]
	ds_read_b128 v[232:235], v198 offset:26176
	ds_read_b128 v[236:239], v198 offset:8768
	s_waitcnt lgkmcnt(4)
	v_mfma_f32_16x16x32_bf16 v[56:59], v[240:243], v[244:247], v[56:59]
	ds_read_b128 v[240:243], v198 offset:26240
	ds_read_b128 v[244:247], v198 offset:8832
	v_mov_b32_e32 v60, s61
	s_nop 6
	v_cndmask_b32_e32 v60, v56, v60, vcc
	v_cndmask_b32_e64 v56, v60, v56, s[44:45]
	v_cndmask_b32_e64 v57, 0, v57, s[44:45]
	v_cndmask_b32_e64 v58, v58, 0, s[46:47]
	v_cndmask_b32_e64 v59, v59, 0, s[48:49]
	v_cvt_pk_bf16_f32 v146, v56, v57
	v_cvt_pk_bf16_f32 v147, v58, v59
	s_waitcnt lgkmcnt(4)
	v_mfma_f32_16x16x32_bf16 v[56:59], v[248:251], v[208:211], 0
	ds_read_b128 v[248:251], v198 offset:26304
	ds_read_b128 v[208:211], v198 offset:8896
	s_waitcnt lgkmcnt(4)
	v_mfma_f32_16x16x32_bf16 v[56:59], v[232:235], v[236:239], v[56:59]
	ds_read_b128 v[232:235], v200 offset:17408
	ds_read_b128 v[236:239], v200
	s_waitcnt lgkmcnt(4)
	v_mfma_f32_16x16x32_bf16 v[56:59], v[240:243], v[244:247], v[56:59]
	ds_read_b128 v[240:243], v200 offset:17472
	ds_read_b128 v[244:247], v200 offset:64
	s_waitcnt lgkmcnt(4)
	v_mfma_f32_16x16x32_bf16 v[56:59], v[248:251], v[208:211], v[56:59]
	ds_read_b128 v[248:251], v200 offset:17536
	ds_read_b128 v[208:211], v200 offset:128
	v_mov_b32_e32 v60, s61
	s_nop 6
	v_cndmask_b32_e32 v60, v56, v60, vcc
	v_cndmask_b32_e64 v56, v60, v56, s[44:45]
	v_cndmask_b32_e64 v57, 0, v57, s[44:45]
	v_cndmask_b32_e64 v58, v58, 0, s[46:47]
	v_cndmask_b32_e64 v59, v59, 0, s[48:49]
	v_cvt_pk_bf16_f32 v142, v56, v57
	v_cvt_pk_bf16_f32 v143, v58, v59
	s_waitcnt lgkmcnt(4)
	v_mfma_f32_16x16x32_bf16 v[56:59], v[232:235], v[236:239], 0
	ds_read_b128 v[232:235], v200 offset:17600
	ds_read_b128 v[236:239], v200 offset:192
	s_waitcnt lgkmcnt(4)
	v_mfma_f32_16x16x32_bf16 v[56:59], v[240:243], v[244:247], v[56:59]
	s_waitcnt lgkmcnt(2)
	v_mfma_f32_16x16x32_bf16 v[56:59], v[248:251], v[208:211], v[56:59]
	s_waitcnt lgkmcnt(0)
	v_mfma_f32_16x16x32_bf16 v[56:59], v[232:235], v[236:239], v[56:59]
	v_mov_b32_e32 v60, s61
	s_nop 6
	v_cndmask_b32_e32 v60, v56, v60, vcc
	v_cndmask_b32_e64 v56, v60, v56, s[44:45]
	v_cndmask_b32_e64 v57, 0, v57, s[44:45]
	v_cndmask_b32_e64 v58, v58, 0, s[46:47]
	v_cndmask_b32_e64 v59, v59, 0, s[48:49]
	v_cvt_pk_bf16_f32 v138, v56, v57
	v_cvt_pk_bf16_f32 v139, v58, v59
	ds_read2_b64 v[116:119], v201 offset1:4
	ds_read2_b64 v[112:115], v201 offset0:8 offset1:12
	ds_read2_b64 v[108:111], v201 offset0:16 offset1:20
	ds_read2_b64 v[104:107], v201 offset0:24 offset1:28
	ds_read_b128 v[100:103], v188 offset:53248
	ds_read_b128 v[96:99], v188 offset:53312
	ds_read_b64_tr_b16 v[184:185], v202 offset:17408
	ds_read_b64_tr_b16 v[166:167], v202 offset:17440
	ds_read_b128 v[92:95], v188 offset:53376
	ds_read_b64_tr_b16 v[164:165], v202 offset:17472
	ds_read_b128 v[88:91], v188 offset:53440
	ds_read_b64_tr_b16 v[162:163], v202 offset:17504
	ds_read_b128 v[72:75], v188 offset:53504
	ds_read_b64_tr_b16 v[160:161], v202 offset:17536
	ds_read_b128 v[64:67], v188 offset:53568
	ds_read_b64_tr_b16 v[158:159], v202 offset:17568
	ds_read_b128 v[60:63], v188 offset:53632
	ds_read_b64_tr_b16 v[156:157], v202 offset:17600
	ds_read_b128 v[56:59], v188 offset:53696
	ds_read_b64_tr_b16 v[154:155], v202 offset:17632
	ds_read2_b64 v[84:87], v68 offset0:32 offset1:36
	ds_read2_b64 v[80:83], v68 offset0:40 offset1:44
	ds_read2_b64 v[76:79], v68 offset0:48 offset1:52
	ds_read2_b64 v[68:71], v68 offset0:56 offset1:60
	v_cvt_pk_bf16_f32 v204, v44, v45
	v_cvt_pk_bf16_f32 v205, v46, v47
	v_cvt_pk_bf16_f32 v206, v52, v53
	v_cvt_pk_bf16_f32 v207, v54, v55
	s_waitcnt lgkmcnt(14)
; #define LAS __attribute__((address_space(3)))
; __device__ __forceinline__ unsigned cvt_pk_bf16(float lo, float hi) { unsigned r; asm volatile("v_cvt_pk_bf16_f32 %0, %1, %2" : "=v"(r) : "v"(lo), "v"(hi)); return r; }
; __device__ __forceinline__ void scan_unit(LAS unsigned char* lds, bf16* UB, bf16* UC, const ScanBufs sb, unsigned* pre_cnt, unsigned pre_want, unsigned* scan_cnt, int type, int bl, int h, int j, int tid, int wave, int lane) {
;     ...
;         for (int cc = 0; cc < 4; ++cc) {
;             const int bi = cc & 1;
;             f32x4 dv[8]; s16x4 ka[8];
; #pragma unroll
;             for (int rb = 0; rb < 8; ++rb) { dv[rb] = *(const LAS f32x4*)(lds + S2_D + (cc * 128 + 16 * rb + 4 * g) * 4); ka[rb] = __builtin_bit_cast(s16x4, __builtin_amdgcn_ds_read_tr16_b64_v4i16((LAS v4i16_t*)(lds + S2_KP + (16 * cc + 4 * g + (x >> 2)) * S2_ROW + (16 * rb + 4 * (x & 3)) * 2))); }
;             if (cc < 3) { if (bi == 0) S2_FETCH(cc + 1, 1); else S2_FETCH(cc + 1, 0); }
;             f32x4 o0 = (f32x4){0.f, 0.f, 0.f, 0.f}, o1 = (f32x4){0.f, 0.f, 0.f, 0.f};
; #pragma unroll
;             for (int i = 0; i < 4; ++i) {
;                 const u32x4 sfw = (u32x4){cvt_pk_bf16(S[2 * i][0], S[2 * i][1]), cvt_pk_bf16(S[2 * i][2], S[2 * i][3]), cvt_pk_bf16(S[2 * i + 1][0], S[2 * i + 1][1]), cvt_pk_bf16(S[2 * i + 1][2], S[2 * i + 1][3])};
;                 const u32x4 qaw = (u32x4){qa[bi][2 * i].x, qa[bi][2 * i].y, qa[bi][2 * i + 1].x, qa[bi][2 * i + 1].y};
;                 if (i & 1) o1 = __builtin_amdgcn_mfma_f32_16x16x32_bf16(__builtin_bit_cast(bf16x8, qaw), __builtin_bit_cast(bf16x8, sfw), o1, 0, 0, 0);
;                 else       o0 = __builtin_amdgcn_mfma_f32_16x16x32_bf16(__builtin_bit_cast(bf16x8, qaw), __builtin_bit_cast(bf16x8, sfw), o0, 0, 0, 0);
;             }
; #pragma unroll
;             for (int rb = 0; rb < 8; ++rb) S[rb] = __builtin_amdgcn_mfma_f32_16x16x16bf16_1k(ka[rb], vf[cc], S[rb], 0, 0, 0) * dv[rb];
;             o0 = __builtin_amdgcn_mfma_f32_16x16x16bf16_1k(sa[cc], vf[cc], o0, 0, 0, 0);
;             o0 = o0 + o1;
; #pragma unroll
;             for (int r = 0; r < 4; ++r) *(LAS unsigned short*)(lds + S2_O + (16 * cc + 4 * g + r) * S2_ROW + (16 * wave + x) * 2) = (unsigned short)(cvt_pk_bf16(o0[r], 0.f) & 0xffffu);
;         }
	v_mfma_f32_16x16x16_bf16 v[44:47], v[184:185], v[152:153], v[44:47]
	v_mfma_f32_16x16x32_bf16 v[116:119], v[116:119], v[204:207], 0
	v_cvt_pk_bf16_f32 v204, v48, v49
	v_cvt_pk_bf16_f32 v205, v50, v51
	v_cvt_pk_bf16_f32 v206, v40, v41
	v_cvt_pk_bf16_f32 v207, v42, v43
	v_mfma_f32_16x16x16_bf16 v[52:55], v[166:167], v[152:153], v[52:55]
	s_nop 5
	v_mul_f32_e64 v46, v102, v46
	v_mul_f32_e64 v47, v103, v47
	v_pk_mul_f32 v[44:45], v[100:101], v[44:45]
	v_mfma_f32_16x16x32_bf16 v[112:115], v[112:115], v[204:207], 0
	v_cvt_pk_bf16_f32 v204, v36, v37
	v_cvt_pk_bf16_f32 v205, v38, v39
	v_cvt_pk_bf16_f32 v206, v28, v29
	v_cvt_pk_bf16_f32 v207, v30, v31
	s_waitcnt lgkmcnt(8)
	v_mfma_f32_16x16x16_bf16 v[28:31], v[158:159], v[152:153], v[28:31]
	v_mul_f32_e64 v54, v98, v54
	v_mul_f32_e64 v55, v99, v55
	v_pk_mul_f32 v[52:53], v[96:97], v[52:53]
	v_mfma_f32_16x16x32_bf16 v[108:111], v[108:111], v[204:207], v[116:119]
	v_cvt_pk_bf16_f32 v116, v32, v33
	v_cvt_pk_bf16_f32 v117, v34, v35
	v_cvt_pk_bf16_f32 v118, v24, v25
	v_cvt_pk_bf16_f32 v119, v26, v27
	s_waitcnt lgkmcnt(4)
	v_mfma_f32_16x16x16_bf16 v[24:27], v[154:155], v[152:153], v[24:27]
	s_nop 1
	v_mul_f32_e64 v66, v66, v30
	v_mul_f32_e64 v67, v67, v31
	v_pk_mul_f32 v[64:65], v[64:65], v[28:29]
	v_mfma_f32_16x16x32_bf16 v[104:107], v[104:107], v[116:119], v[112:115]
	v_mfma_f32_16x16x16_bf16 v[28:31], v[156:157], v[152:153], v[32:35]
	s_nop 2
	v_mul_f32_e64 v34, v58, v26
	v_mul_f32_e64 v35, v59, v27
	v_pk_mul_f32 v[32:33], v[56:57], v[24:25]
	v_mfma_f32_16x16x16_bf16 v[24:27], v[150:151], v[152:153], v[108:111]
	v_mfma_f32_16x16x16_bf16 v[48:51], v[164:165], v[152:153], v[48:51]
	v_mfma_f32_16x16x16_bf16 v[40:43], v[162:163], v[152:153], v[40:43]
	s_nop 5
	v_add_f32_e64 v24, v104, v24
	v_add_f32_e64 v25, v105, v25
	v_pk_add_f32 v[26:27], v[106:107], v[26:27]
	v_cvt_pk_bf16_f32 v24, v24, v169
	v_mfma_f32_16x16x16_bf16 v[36:39], v[160:161], v[152:153], v[36:39]
	ds_write_b16 v193, v24 offset:55296
	v_cvt_pk_bf16_f32 v24, v25, v169
	ds_write_b16 v193, v24 offset:55568
	v_cvt_pk_bf16_f32 v24, v26, v169
	ds_write_b16 v203, v24 offset:55296
	v_cvt_pk_bf16_f32 v24, v27, v169
	ds_write_b16 v203, v24 offset:55568
	v_add_u32_e32 v24, 0x2000, v201
	v_pk_mul_f32 v[94:95], v[94:95], v[50:51]
	v_pk_mul_f32 v[92:93], v[92:93], v[48:49]
	v_pk_mul_f32 v[42:43], v[90:91], v[42:43]
	v_pk_mul_f32 v[40:41], v[88:89], v[40:41]
	v_pk_mul_f32 v[74:75], v[74:75], v[38:39]
	v_pk_mul_f32 v[72:73], v[72:73], v[36:37]
	v_pk_mul_f32 v[90:91], v[62:63], v[30:31]
	v_pk_mul_f32 v[88:89], v[60:61], v[28:29]
	ds_read_b128 v[56:59], v188 offset:53760
	ds_read_b128 v[60:63], v188 offset:53824
	ds_read_b64_tr_b16 v[162:163], v202 offset:21760
	ds_read_b64_tr_b16 v[164:165], v202 offset:21792
	ds_read_b128 v[108:111], v188 offset:53888
	ds_read_b64_tr_b16 v[166:167], v202 offset:21824
	ds_read_b128 v[112:115], v188 offset:53952
	ds_read_b64_tr_b16 v[170:171], v202 offset:21856
	ds_read_b128 v[116:119], v188 offset:54016
	ds_read_b64_tr_b16 v[172:173], v202 offset:21888
	ds_read_b128 v[150:153], v188 offset:54080
	ds_read_b64_tr_b16 v[184:185], v202 offset:21920
	ds_read_b128 v[100:103], v188 offset:54144
	ds_read_b64_tr_b16 v[106:107], v202 offset:21952
	ds_read_b128 v[96:99], v188 offset:54208
	ds_read_b64_tr_b16 v[104:105], v202 offset:21984
	ds_read2_b64 v[48:51], v24 offset0:64 offset1:68
	ds_read2_b64 v[36:39], v24 offset0:72 offset1:76
	ds_read2_b64 v[28:31], v24 offset0:80 offset1:84
	ds_read2_b64 v[24:27], v24 offset0:88 offset1:92
	v_cvt_pk_bf16_f32 v154, v44, v45
	v_cvt_pk_bf16_f32 v155, v46, v47
	v_cvt_pk_bf16_f32 v156, v52, v53
	v_cvt_pk_bf16_f32 v157, v54, v55
	s_waitcnt lgkmcnt(14)
	v_mfma_f32_16x16x16_bf16 v[44:47], v[162:163], v[148:149], v[44:47]
	v_mfma_f32_16x16x32_bf16 v[84:87], v[84:87], v[154:157], 0
	v_cvt_pk_bf16_f32 v154, v92, v93
	v_cvt_pk_bf16_f32 v155, v94, v95
	v_cvt_pk_bf16_f32 v156, v40, v41
	v_cvt_pk_bf16_f32 v157, v42, v43
	s_waitcnt lgkmcnt(12)
	v_mfma_f32_16x16x16_bf16 v[40:43], v[170:171], v[148:149], v[40:43]
	v_mfma_f32_16x16x32_bf16 v[80:83], v[80:83], v[154:157], 0
	v_cvt_pk_bf16_f32 v154, v72, v73
	v_cvt_pk_bf16_f32 v155, v74, v75
	v_cvt_pk_bf16_f32 v156, v64, v65
	v_cvt_pk_bf16_f32 v157, v66, v67
	s_nop 0
	v_mfma_f32_16x16x32_bf16 v[154:157], v[76:79], v[154:157], v[84:87]
	v_cvt_pk_bf16_f32 v76, v88, v89
	v_cvt_pk_bf16_f32 v77, v90, v91
	v_cvt_pk_bf16_f32 v78, v32, v33
	v_cvt_pk_bf16_f32 v79, v34, v35
	s_waitcnt lgkmcnt(4)
; #define LAS __attribute__((address_space(3)))
; __device__ __forceinline__ unsigned cvt_pk_bf16(float lo, float hi) { unsigned r; asm volatile("v_cvt_pk_bf16_f32 %0, %1, %2" : "=v"(r) : "v"(lo), "v"(hi)); return r; }
; __device__ __forceinline__ void scan_unit(LAS unsigned char* lds, bf16* UB, bf16* UC, const ScanBufs sb, unsigned* pre_cnt, unsigned pre_want, unsigned* scan_cnt, int type, int bl, int h, int j, int tid, int wave, int lane) {
;     ...
;         for (int cc = 0; cc < 4; ++cc) {
;             const int bi = cc & 1;
;             f32x4 dv[8]; s16x4 ka[8];
; #pragma unroll
;             for (int rb = 0; rb < 8; ++rb) { dv[rb] = *(const LAS f32x4*)(lds + S2_D + (cc * 128 + 16 * rb + 4 * g) * 4); ka[rb] = __builtin_bit_cast(s16x4, __builtin_amdgcn_ds_read_tr16_b64_v4i16((LAS v4i16_t*)(lds + S2_KP + (16 * cc + 4 * g + (x >> 2)) * S2_ROW + (16 * rb + 4 * (x & 3)) * 2))); }
;             if (cc < 3) { if (bi == 0) S2_FETCH(cc + 1, 1); else S2_FETCH(cc + 1, 0); }
;             f32x4 o0 = (f32x4){0.f, 0.f, 0.f, 0.f}, o1 = (f32x4){0.f, 0.f, 0.f, 0.f};
; #pragma unroll
;             for (int i = 0; i < 4; ++i) {
;                 const u32x4 sfw = (u32x4){cvt_pk_bf16(S[2 * i][0], S[2 * i][1]), cvt_pk_bf16(S[2 * i][2], S[2 * i][3]), cvt_pk_bf16(S[2 * i + 1][0], S[2 * i + 1][1]), cvt_pk_bf16(S[2 * i + 1][2], S[2 * i + 1][3])};
;                 const u32x4 qaw = (u32x4){qa[bi][2 * i].x, qa[bi][2 * i].y, qa[bi][2 * i + 1].x, qa[bi][2 * i + 1].y};
;                 if (i & 1) o1 = __builtin_amdgcn_mfma_f32_16x16x32_bf16(__builtin_bit_cast(bf16x8, qaw), __builtin_bit_cast(bf16x8, sfw), o1, 0, 0, 0);
;                 else       o0 = __builtin_amdgcn_mfma_f32_16x16x32_bf16(__builtin_bit_cast(bf16x8, qaw), __builtin_bit_cast(bf16x8, sfw), o0, 0, 0, 0);
;             }
; #pragma unroll
;             for (int rb = 0; rb < 8; ++rb) S[rb] = __builtin_amdgcn_mfma_f32_16x16x16bf16_1k(ka[rb], vf[cc], S[rb], 0, 0, 0) * dv[rb];
;             o0 = __builtin_amdgcn_mfma_f32_16x16x16bf16_1k(sa[cc], vf[cc], o0, 0, 0, 0);
;             o0 = o0 + o1;
; #pragma unroll
;             for (int r = 0; r < 4; ++r) *(LAS unsigned short*)(lds + S2_O + (16 * cc + 4 * g + r) * S2_ROW + (16 * wave + x) * 2) = (unsigned short)(cvt_pk_bf16(o0[r], 0.f) & 0xffffu);
;         }
	v_mfma_f32_16x16x16_bf16 v[32:35], v[104:105], v[148:149], v[32:35]
	s_nop 0
	v_mul_f32_e64 v86, v58, v46
	v_mul_f32_e64 v87, v59, v47
	v_pk_mul_f32 v[84:85], v[56:57], v[44:45]
	v_mfma_f32_16x16x32_bf16 v[158:161], v[68:71], v[76:79], v[80:83]
	v_mul_f32_e64 v70, v114, v42
	v_mul_f32_e64 v71, v115, v43
	v_pk_mul_f32 v[68:69], v[112:113], v[40:41]
	v_mfma_f32_16x16x16_bf16 v[44:47], v[164:165], v[148:149], v[52:55]
	v_mfma_f32_16x16x16_bf16 v[40:43], v[172:173], v[148:149], v[72:75]
	s_nop 6
	v_mul_f32_e64 v82, v62, v46
	v_mul_f32_e64 v83, v63, v47
	v_pk_mul_f32 v[80:81], v[60:61], v[44:45]
	v_pk_mul_f32 v[62:63], v[118:119], v[42:43]
	v_pk_mul_f32 v[60:61], v[116:117], v[40:41]
	v_mfma_f32_16x16x16_bf16 v[40:43], v[184:185], v[148:149], v[64:67]
	s_nop 2
	v_mul_f32_e64 v66, v98, v34
	v_mul_f32_e64 v67, v99, v35
	v_pk_mul_f32 v[64:65], v[96:97], v[32:33]
	v_mfma_f32_16x16x16_bf16 v[32:35], v[146:147], v[148:149], v[154:157]
	s_nop 0
	v_mul_f32_e64 v58, v152, v42
	v_mul_f32_e64 v59, v153, v43
	v_pk_mul_f32 v[56:57], v[150:151], v[40:41]
	v_mfma_f32_16x16x16_bf16 v[44:47], v[166:167], v[148:149], v[92:95]
	v_mfma_f32_16x16x16_bf16 v[40:43], v[106:107], v[148:149], v[88:91]
	s_nop 1
	v_add_f32_e64 v32, v158, v32
	v_add_f32_e64 v33, v159, v33
	v_pk_add_f32 v[34:35], v[160:161], v[34:35]
	v_cvt_pk_bf16_f32 v32, v32, v169
	ds_write_b16 v193, v32 offset:59648
	v_cvt_pk_bf16_f32 v32, v33, v169
	ds_write_b16 v193, v32 offset:59920
	v_cvt_pk_bf16_f32 v32, v34, v169
	ds_write_b16 v193, v32 offset:60192
	v_cvt_pk_bf16_f32 v32, v35, v169
	ds_write_b16 v193, v32 offset:60464
	v_add_u32_e32 v32, 0x3000, v201
	v_pk_mul_f32 v[78:79], v[110:111], v[46:47]
	v_pk_mul_f32 v[76:77], v[108:109], v[44:45]
	v_pk_mul_f32 v[74:75], v[102:103], v[42:43]
	v_pk_mul_f32 v[72:73], v[100:101], v[40:41]
	ds_read_b128 v[100:103], v188 offset:54272
	ds_read_b128 v[104:107], v188 offset:54336
	ds_read_b64_tr_b16 v[154:155], v202 offset:26112
	ds_read_b64_tr_b16 v[156:157], v202 offset:26144
	ds_read_b128 v[108:111], v188 offset:54400
	ds_read_b64_tr_b16 v[158:159], v202 offset:26176
	ds_read_b128 v[112:115], v188 offset:54464
	ds_read_b64_tr_b16 v[160:161], v202 offset:26208
	ds_read_b128 v[116:119], v188 offset:54528
	ds_read_b64_tr_b16 v[162:163], v202 offset:26240
	ds_read_b128 v[146:149], v188 offset:54592
	ds_read_b64_tr_b16 v[164:165], v202 offset:26272
	ds_read_b128 v[92:95], v188 offset:54656
	ds_read_b64_tr_b16 v[98:99], v202 offset:26304
	ds_read_b128 v[88:91], v188 offset:54720
	ds_read_b64_tr_b16 v[96:97], v202 offset:26336
	ds_read2_b64 v[52:55], v32 offset0:96 offset1:100
	ds_read2_b64 v[44:47], v32 offset0:104 offset1:108
	ds_read2_b64 v[40:43], v32 offset0:112 offset1:116
	ds_read2_b64 v[32:35], v32 offset0:120 offset1:124
	v_cvt_pk_bf16_f32 v150, v84, v85
	v_cvt_pk_bf16_f32 v151, v86, v87
	v_cvt_pk_bf16_f32 v152, v80, v81
	v_cvt_pk_bf16_f32 v153, v82, v83
	s_waitcnt lgkmcnt(14)
	v_mfma_f32_16x16x32_bf16 v[48:51], v[48:51], v[150:153], 0
	v_cvt_pk_bf16_f32 v150, v76, v77
	v_cvt_pk_bf16_f32 v151, v78, v79
	v_cvt_pk_bf16_f32 v152, v68, v69
	v_cvt_pk_bf16_f32 v153, v70, v71
	s_waitcnt lgkmcnt(12)
	v_mfma_f32_16x16x16_bf16 v[68:71], v[160:161], v[144:145], v[68:71]
	v_mfma_f32_16x16x32_bf16 v[36:39], v[36:39], v[150:153], 0
	v_cvt_pk_bf16_f32 v150, v60, v61
	v_cvt_pk_bf16_f32 v151, v62, v63
	v_cvt_pk_bf16_f32 v152, v56, v57
	v_cvt_pk_bf16_f32 v153, v58, v59
	s_waitcnt lgkmcnt(10)
	v_mfma_f32_16x16x16_bf16 v[60:63], v[162:163], v[144:145], v[60:63]
	s_nop 4
	v_mul_f32_e64 v70, v114, v70
	v_mul_f32_e64 v71, v115, v71
	v_pk_mul_f32 v[68:69], v[112:113], v[68:69]
	v_mfma_f32_16x16x32_bf16 v[48:51], v[28:31], v[150:153], v[48:51]
	v_cvt_pk_bf16_f32 v28, v72, v73
	v_cvt_pk_bf16_f32 v29, v74, v75
	v_cvt_pk_bf16_f32 v30, v64, v65
	v_cvt_pk_bf16_f32 v31, v66, v67
	v_mfma_f32_16x16x16_bf16 v[48:51], v[142:143], v[144:145], v[48:51]
	v_mul_f32_e64 v62, v118, v62
	v_mul_f32_e64 v63, v119, v63
	v_pk_mul_f32 v[60:61], v[116:117], v[60:61]
	v_mfma_f32_16x16x32_bf16 v[150:153], v[24:27], v[28:31], v[36:39]
	v_mfma_f32_16x16x16_bf16 v[24:27], v[154:155], v[144:145], v[84:87]
	v_mfma_f32_16x16x16_bf16 v[28:31], v[156:157], v[144:145], v[80:83]
	s_nop 5
	v_add_f32_e64 v48, v150, v48
	v_add_f32_e64 v49, v151, v49
	v_pk_add_f32 v[50:51], v[152:153], v[50:51]
	v_cvt_pk_bf16_f32 v48, v48, v169
	s_waitcnt lgkmcnt(8)
	v_mfma_f32_16x16x16_bf16 v[56:59], v[164:165], v[144:145], v[56:59]
	ds_write_b16 v193, v48 offset:64000
	v_cvt_pk_bf16_f32 v48, v49, v169
	ds_write_b16 v193, v48 offset:64272
	s_waitcnt lgkmcnt(8)
	v_mfma_f32_16x16x16_bf16 v[72:75], v[98:99], v[144:145], v[72:75]
	v_cvt_pk_bf16_f32 v48, v50, v169
	ds_write_b16 v193, v48 offset:64544
	v_cvt_pk_bf16_f32 v48, v51, v169
	s_waitcnt lgkmcnt(7)
; #define LAS __attribute__((address_space(3)))
; __device__ __forceinline__ void scan_unit(LAS unsigned char* lds, bf16* UB, bf16* UC, const ScanBufs sb, unsigned* pre_cnt, unsigned pre_want, unsigned* scan_cnt, int type, int bl, int h, int j, int tid, int wave, int lane) {
;     ...
;         for (int cc = 0; cc < 4; ++cc) {
;             const int bi = cc & 1;
;             f32x4 dv[8]; s16x4 ka[8];
; #pragma unroll
;             for (int rb = 0; rb < 8; ++rb) { dv[rb] = *(const LAS f32x4*)(lds + S2_D + (cc * 128 + 16 * rb + 4 * g) * 4); ka[rb] = __builtin_bit_cast(s16x4, __builtin_amdgcn_ds_read_tr16_b64_v4i16((LAS v4i16_t*)(lds + S2_KP + (16 * cc + 4 * g + (x >> 2)) * S2_ROW + (16 * rb + 4 * (x & 3)) * 2))); }
;             if (cc < 3) { if (bi == 0) S2_FETCH(cc + 1, 1); else S2_FETCH(cc + 1, 0); }
;             f32x4 o0 = (f32x4){0.f, 0.f, 0.f, 0.f}, o1 = (f32x4){0.f, 0.f, 0.f, 0.f};
; #pragma unroll
;             for (int i = 0; i < 4; ++i) {
;                 const u32x4 sfw = (u32x4){cvt_pk_bf16(S[2 * i][0], S[2 * i][1]), cvt_pk_bf16(S[2 * i][2], S[2 * i][3]), cvt_pk_bf16(S[2 * i + 1][0], S[2 * i + 1][1]), cvt_pk_bf16(S[2 * i + 1][2], S[2 * i + 1][3])};
;                 const u32x4 qaw = (u32x4){qa[bi][2 * i].x, qa[bi][2 * i].y, qa[bi][2 * i + 1].x, qa[bi][2 * i + 1].y};
;                 if (i & 1) o1 = __builtin_amdgcn_mfma_f32_16x16x32_bf16(__builtin_bit_cast(bf16x8, qaw), __builtin_bit_cast(bf16x8, sfw), o1, 0, 0, 0);
;                 else       o0 = __builtin_amdgcn_mfma_f32_16x16x32_bf16(__builtin_bit_cast(bf16x8, qaw), __builtin_bit_cast(bf16x8, sfw), o0, 0, 0, 0);
;             }
; #pragma unroll
;             for (int rb = 0; rb < 8; ++rb) S[rb] = __builtin_amdgcn_mfma_f32_16x16x16bf16_1k(ka[rb], vf[cc], S[rb], 0, 0, 0) * dv[rb];
;             o0 = __builtin_amdgcn_mfma_f32_16x16x16bf16_1k(sa[cc], vf[cc], o0, 0, 0, 0);
;             o0 = o0 + o1;
; #pragma unroll
;             for (int r = 0; r < 4; ++r) *(LAS unsigned short*)(lds + S2_O + (16 * cc + 4 * g + r) * S2_ROW + (16 * wave + x) * 2) = (unsigned short)(cvt_pk_bf16(o0[r], 0.f) & 0xffffu);
;         }
;     ...
;         __syncthreads();
; #pragma unroll
;         for (int k = 0; k < 2; ++k) { const int ch = tid + 512 * k, row = ch >> 4, c16 = ch & 15;
;             st_wt128(vdst + (rowb + (size_t)tb * 64 + row) * ld + c16 * 8, *(const LAS u32x4*)(lds + S2_O + row * S2_ROW + c16 * 16)); }
	v_mfma_f32_16x16x16_bf16 v[64:67], v[96:97], v[144:145], v[64:67]
	ds_write_b16 v193, v48 offset:64816
	v_pk_mul_f32 v[26:27], v[102:103], v[26:27]
	v_pk_mul_f32 v[24:25], v[100:101], v[24:25]
	v_mfma_f32_16x16x16_bf16 v[36:39], v[158:159], v[144:145], v[76:79]
	v_mul_f32_e64 v30, v106, v30
	v_mul_f32_e64 v31, v107, v31
	v_pk_mul_f32 v[28:29], v[104:105], v[28:29]
	v_pk_mul_f32 v[58:59], v[148:149], v[58:59]
	v_pk_mul_f32 v[56:57], v[146:147], v[56:57]
	v_pk_mul_f32 v[74:75], v[94:95], v[74:75]
	v_pk_mul_f32 v[72:73], v[92:93], v[72:73]
	v_pk_mul_f32 v[66:67], v[90:91], v[66:67]
	v_pk_mul_f32 v[64:65], v[88:89], v[64:65]
	ds_read_b128 v[48:51], v188 offset:54784
	ds_read_b128 v[76:79], v188 offset:54848
	ds_read_b64_tr_b16 v[112:113], v202 offset:30464
	ds_read_b64_tr_b16 v[114:115], v202 offset:30496
	ds_read_b128 v[80:83], v188 offset:54912
	ds_read_b64_tr_b16 v[116:117], v202 offset:30528
	ds_read_b128 v[84:87], v188 offset:54976
	ds_read_b64_tr_b16 v[118:119], v202 offset:30560
	ds_read_b128 v[88:91], v188 offset:55040
	ds_read_b64_tr_b16 v[142:143], v202 offset:30592
	ds_read_b128 v[92:95], v188 offset:55104
	ds_read_b64_tr_b16 v[144:145], v202 offset:30624
	ds_read_b128 v[96:99], v188 offset:55168
	ds_read_b64_tr_b16 v[146:147], v202 offset:30656
	ds_read_b128 v[100:103], v188 offset:55232
	ds_read_b64_tr_b16 v[148:149], v202 offset:30688
	v_cvt_pk_bf16_f32 v104, v24, v25
	v_cvt_pk_bf16_f32 v105, v26, v27
	v_cvt_pk_bf16_f32 v106, v28, v29
	v_cvt_pk_bf16_f32 v107, v30, v31
	v_pk_mul_f32 v[38:39], v[110:111], v[38:39]
	v_pk_mul_f32 v[36:37], v[108:109], v[36:37]
	s_waitcnt lgkmcnt(14)
	v_mfma_f32_16x16x32_bf16 v[52:55], v[52:55], v[104:107], 0
	v_cvt_pk_bf16_f32 v104, v36, v37
	v_cvt_pk_bf16_f32 v105, v38, v39
	v_cvt_pk_bf16_f32 v106, v68, v69
	v_cvt_pk_bf16_f32 v107, v70, v71
	s_waitcnt lgkmcnt(13)
	v_mfma_f32_16x16x16_bf16 v[24:27], v[112:113], v[140:141], v[24:27]
	v_mfma_f32_16x16x32_bf16 v[44:47], v[44:47], v[104:107], 0
	v_cvt_pk_bf16_f32 v104, v60, v61
	v_cvt_pk_bf16_f32 v105, v62, v63
	v_cvt_pk_bf16_f32 v106, v56, v57
	v_cvt_pk_bf16_f32 v107, v58, v59
	s_nop 0
	v_mfma_f32_16x16x32_bf16 v[104:107], v[40:43], v[104:107], v[52:55]
	v_cvt_pk_bf16_f32 v40, v72, v73
	v_cvt_pk_bf16_f32 v41, v74, v75
	v_cvt_pk_bf16_f32 v42, v64, v65
	v_cvt_pk_bf16_f32 v43, v66, v67
	s_nop 0
	v_mfma_f32_16x16x32_bf16 v[108:111], v[32:35], v[40:43], v[44:47]
	s_nop 3
	v_mul_f32_e64 v46, v50, v26
	v_mul_f32_e64 v47, v51, v27
	v_pk_mul_f32 v[44:45], v[48:49], v[24:25]
	s_waitcnt lgkmcnt(12)
	v_mfma_f32_16x16x16_bf16 v[24:27], v[114:115], v[140:141], v[28:31]
	s_nop 7
	v_pk_mul_f32 v[54:55], v[78:79], v[26:27]
	v_pk_mul_f32 v[52:53], v[76:77], v[24:25]
	s_waitcnt lgkmcnt(10)
	v_mfma_f32_16x16x16_bf16 v[24:27], v[116:117], v[140:141], v[36:39]
	s_nop 7
	v_pk_mul_f32 v[50:51], v[82:83], v[26:27]
	v_pk_mul_f32 v[48:49], v[80:81], v[24:25]
	s_waitcnt lgkmcnt(8)
	v_mfma_f32_16x16x16_bf16 v[24:27], v[118:119], v[140:141], v[68:71]
	s_nop 7
	v_pk_mul_f32 v[42:43], v[86:87], v[26:27]
	v_pk_mul_f32 v[40:41], v[84:85], v[24:25]
	s_waitcnt lgkmcnt(6)
	v_mfma_f32_16x16x16_bf16 v[24:27], v[142:143], v[140:141], v[60:63]
	s_nop 2
	v_lshl_add_u64 v[60:61], v[136:137], 0, s[12:13]
	v_add_co_u32_e64 v60, s[52:53], s51, v60
	s_nop 2
	v_pk_mul_f32 v[38:39], v[90:91], v[26:27]
	v_pk_mul_f32 v[36:37], v[88:89], v[24:25]
	s_waitcnt lgkmcnt(4)
	v_mfma_f32_16x16x16_bf16 v[24:27], v[144:145], v[140:141], v[56:59]
	v_addc_co_u32_e64 v61, s[52:53], 0, v61, s[52:53]
	v_mfma_f32_16x16x16_bf16 v[56:59], v[138:139], v[140:141], v[104:107]
	s_nop 5
	v_mul_f32_e64 v30, v94, v26
	v_mul_f32_e64 v31, v95, v27
	v_pk_add_f32 v[56:57], v[108:109], v[56:57]
	v_pk_add_f32 v[58:59], v[110:111], v[58:59]
	v_cvt_pk_bf16_f32 v56, v56, v169
	ds_write_b16 v194, v56 offset:13056
	v_cvt_pk_bf16_f32 v56, v57, v169
	ds_write_b16 v194, v56 offset:13328
	v_cvt_pk_bf16_f32 v56, v58, v169
	ds_write_b16 v194, v56 offset:13600
	v_cvt_pk_bf16_f32 v56, v59, v169
	ds_write_b16 v194, v56 offset:13872
	v_add_u32_e32 v56, v189, v190
	s_waitcnt lgkmcnt(0)
	s_barrier
	ds_read_b128 v[56:59], v56 offset:55296
	v_pk_mul_f32 v[28:29], v[92:93], v[24:25]
	v_mfma_f32_16x16x16_bf16 v[24:27], v[146:147], v[140:141], v[72:75]
	s_waitcnt lgkmcnt(0)
	global_store_dwordx2 v[60:61], v[56:57], off sc1
	global_store_dwordx2 v[60:61], v[58:59], off offset:8 sc1
	v_add_u32_e32 v56, v189, v191
	s_nop 3
	v_pk_mul_f32 v[34:35], v[98:99], v[26:27]
	v_pk_mul_f32 v[32:33], v[96:97], v[24:25]
	v_mfma_f32_16x16x16_bf16 v[24:27], v[148:149], v[140:141], v[64:67]
	ds_read_b128 v[56:59], v56 offset:55296
	v_lshl_add_u64 v[60:61], v[134:135], 0, s[12:13]
	s_add_u32 s12, s12, 0x80000
	v_add_co_u32_e64 v60, s[52:53], s51, v60
	s_addc_u32 s13, s13, 0
	s_add_i32 s60, s60, 64
	s_nop 1
	v_pk_mul_f32 v[26:27], v[102:103], v[26:27]
	v_pk_mul_f32 v[24:25], v[100:101], v[24:25]
	v_addc_co_u32_e64 v61, s[52:53], 0, v61, s[52:53]
	s_cmp_eq_u32 s12, 0x2000000
	s_waitcnt lgkmcnt(0)
	global_store_dwordx2 v[60:61], v[56:57], off sc1
	global_store_dwordx2 v[60:61], v[58:59], off offset:8 sc1
	s_cbranch_scc1 .LBB0_574
